# v6: forget-gate blocks rewritten (gathered lr load, SALU unpack, SGPR-operand fma chains, trimmed log path) + M3 item re-assignment + earlier load de-serialization
# speedup vs baseline: 1.0286x; 1.0286x over previous
; template <bool FINAL>
; DI void gla_unit(KA a, int l, int item, LAS unsigned char* lds) {
;     ...
;     {
;         float wg[2][16], bg[2];
; #pragma unroll
;         for (int hh = 0; hh < 2; ++hh) {
;             const float* wg2 = a->in[18] + (size_t)l * 16 * 256 + (2 * hp + hh) * 64 + dk;
; #pragma unroll
;             for (int e = 0; e < 16; ++e) wg[hh][e] = wg2[e * 256];
;             bg[hh] = a->in[19][l * 256 + (2 * hp + hh) * 64 + dk];
;         }
;         float run0 = 0.f, run1 = 0.f;
; #pragma unroll
;         for (int jj = 0; jj < 8; ++jj) {
;             const int t = 8 * tg + jj;
;             float ga = 0.f, gb = 0.f;
;             if (t < nvalid) {
;                 const u32x4* lp = (const u32x4*)(U + (size_t)(row0 + t) * UN + U_LR);
;                 float lr[16]; unpack8(lp[0], lr); unpack8(lp[1], lr + 8);
;                 float za = bg[0], zb = bg[1];
; #pragma unroll
;                 for (int e = 0; e < 16; ++e) { za += wg[0][e] * lr[e]; zb += wg[1][e] * lr[e]; }
;                 ga = (fminf(za, 0.f) - __logf(1.f + __expf(-fabsf(za)))) * (1.f / 16.f);
;                 gb = (fminf(zb, 0.f) - __logf(1.f + __expf(-fabsf(zb)))) * (1.f / 16.f);
;             }
;             run0 += ga; run1 += gb; bl[0][jj] = run0; bl[1][jj] = run1;
.LBB0_649:
	s_load_dwordx4 s[4:7], s[2:3], 0x90
	v_readlane_b32 s24, v255, 1
	v_readlane_b32 s25, v255, 2
	s_lshl_b64 s[24:25], s[24:25], 2
	v_lshlrev_b32_e32 v144, 2, v75
	s_waitcnt lgkmcnt(0)
	s_add_u32 s4, s4, s24
	s_addc_u32 s5, s5, s25
	v_readlane_b32 s0, v255, 3
	v_lshl_add_u64 v[16:17], s[4:5], 0, v[144:145]
	v_mov_b32_e32 v29, v145
	v_or_b32_e32 v44, s0, v75
	s_lshl_b32 s0, s60, 2
	v_lshl_add_u64 v[16:17], v[16:17], 0, s[0:1]
	s_movk_i32 s0, 0x1000
	v_add_co_u32_e32 v18, vcc, s0, v16
	s_movk_i32 s0, 0x2000
	s_nop 0
	v_addc_co_u32_e32 v19, vcc, 0, v17, vcc
	v_add_co_u32_e32 v20, vcc, s0, v16
	s_movk_i32 s0, 0x3000
	s_nop 0
	v_addc_co_u32_e32 v21, vcc, 0, v17, vcc
	v_add_co_u32_e32 v42, vcc, s0, v16
	v_or_b32_e32 v28, s60, v44
	s_nop 0
	v_addc_co_u32_e32 v43, vcc, 0, v17, vcc
	v_lshl_add_u64 v[28:29], v[28:29], 2, s[6:7]
	global_load_dword v112, v[16:17], off
	global_load_dword v111, v[16:17], off offset:1024
	global_load_dword v110, v[16:17], off offset:2048
	global_load_dword v109, v[16:17], off offset:3072
	global_load_dword v115, v[20:21], off offset:-4096
	global_load_dword v114, v[18:19], off offset:1024
	global_load_dword v33, v[18:19], off offset:2048
	global_load_dword v32, v[18:19], off offset:3072
	global_load_dword v31, v[20:21], off
	global_load_dword v30, v[20:21], off offset:1024
	global_load_dword v27, v[20:21], off offset:2048
	global_load_dword v26, v[20:21], off offset:3072
	global_load_dword v25, v[42:43], off
	global_load_dword v24, v[42:43], off offset:1024
	global_load_dword v23, v[42:43], off offset:2048
	global_load_dword v22, v[42:43], off offset:3072
	global_load_dword v113, v[28:29], off
	global_load_dword v118, v[16:17], off offset:256
	global_load_dword v117, v[16:17], off offset:1280
	global_load_dword v116, v[16:17], off offset:2304
	global_load_dword v121, v[16:17], off offset:3328
	global_load_dword v120, v[18:19], off offset:256
	global_load_dword v119, v[18:19], off offset:1280
	global_load_dword v41, v[18:19], off offset:2304
	global_load_dword v40, v[18:19], off offset:3328
	global_load_dword v39, v[20:21], off offset:256
	global_load_dword v38, v[20:21], off offset:1280
	global_load_dword v37, v[20:21], off offset:2304
	global_load_dword v36, v[20:21], off offset:3328
	global_load_dword v35, v[42:43], off offset:256
	global_load_dword v34, v[42:43], off offset:1280
	global_load_dword v29, v[42:43], off offset:2304
	global_load_dword v28, v[42:43], off offset:3328
	v_add_u32_e32 v16, s60, v44
	v_mov_b32_e32 v17, v145
	v_lshl_add_u64 v[16:17], v[16:17], 2, s[6:7]
	global_load_dword v122, v[16:17], off offset:256
	v_lshrrev_b32_e32 v128, 3, v75
	v_mul_u32_u24_e32 v128, 0x1600, v128
	v_and_b32_e32 v129, 7, v75
	v_lshl_add_u32 v128, v129, 2, v128
	s_add_i32 s72, s59, s51
	s_mul_hi_i32 s73, s72, 0x1600
	s_mulk_i32 s72, 0x1600
	s_add_u32 s72, s34, s72
	s_addc_u32 s73, s35, s73
	s_add_u32 s72, s72, 0x1400
	s_addc_u32 s73, s73, 0
	global_load_dword v129, v128, s[72:73]
	v_mov_b32_e32 v42, 0
	s_and_b64 vcc, exec, s[22:23]
	v_mov_b32_e32 v20, 0
	v_mov_b32_e32 v21, 0
	s_cbranch_vccnz .LBB0_651
	s_add_i32 s0, s59, s51
	s_mul_hi_i32 s5, s0, 0x1600
	s_mulk_i32 s0, 0x1600
	s_add_u32 s4, s34, s0
	s_addc_u32 s5, s35, s5
	s_add_u32 s6, s4, 0x1400
	s_addc_u32 s7, s5, 0
	s_mov_b32 s96, 0xbfb8aa3b
	s_mov_b32 s97, 0x3f317217
	s_waitcnt vmcnt(0)
	v_readlane_b32 s72, v129, 0
	v_readlane_b32 s73, v129, 1
	v_readlane_b32 s74, v129, 2
	v_readlane_b32 s75, v129, 3
	v_readlane_b32 s76, v129, 4
	v_readlane_b32 s77, v129, 5
	v_readlane_b32 s78, v129, 6
	v_readlane_b32 s79, v129, 7
	s_lshl_b32 s80, s72, 16
	s_and_b32 s81, s72, 0xffff0000
	s_lshl_b32 s82, s73, 16
	s_and_b32 s83, s73, 0xffff0000
	s_lshl_b32 s84, s74, 16
	s_and_b32 s85, s74, 0xffff0000
	s_lshl_b32 s86, s75, 16
	s_and_b32 s87, s75, 0xffff0000
	s_lshl_b32 s88, s76, 16
	s_and_b32 s89, s76, 0xffff0000
	s_lshl_b32 s90, s77, 16
	s_and_b32 s91, s77, 0xffff0000
	s_lshl_b32 s92, s78, 16
	s_and_b32 s93, s78, 0xffff0000
	s_lshl_b32 s94, s79, 16
	s_and_b32 s95, s79, 0xffff0000
	v_fma_f32 v16, v112, s80, v113
	v_fma_f32 v17, v118, s80, v122
	v_fmac_f32_e32 v16, s81, v111
	v_fmac_f32_e32 v17, s81, v117
	v_fmac_f32_e32 v16, s82, v110
	v_fmac_f32_e32 v17, s82, v116
	v_fmac_f32_e32 v16, s83, v109
	v_fmac_f32_e32 v17, s83, v121
	v_fmac_f32_e32 v16, s84, v115
	v_fmac_f32_e32 v17, s84, v120
	v_fmac_f32_e32 v16, s85, v114
	v_fmac_f32_e32 v17, s85, v119
	v_fmac_f32_e32 v16, s86, v33
	v_fmac_f32_e32 v17, s86, v41
	v_fmac_f32_e32 v16, s87, v32
	v_fmac_f32_e32 v17, s87, v40
	v_fmac_f32_e32 v16, s88, v31
	v_fmac_f32_e32 v17, s88, v39
	v_fmac_f32_e32 v16, s89, v30
	v_fmac_f32_e32 v17, s89, v38
	v_fmac_f32_e32 v16, s90, v27
	v_fmac_f32_e32 v17, s90, v37
	v_fmac_f32_e32 v16, s91, v26
	v_fmac_f32_e32 v17, s91, v36
	v_fmac_f32_e32 v16, s92, v25
	v_fmac_f32_e32 v17, s92, v35
	v_fmac_f32_e32 v16, s93, v24
	v_fmac_f32_e32 v17, s93, v34
	v_fmac_f32_e32 v16, s94, v23
	v_fmac_f32_e32 v17, s94, v29
	v_fmac_f32_e32 v16, s95, v22
	v_fmac_f32_e32 v17, s95, v28
	v_mul_f32_e64 v18, |v16|, s96
	v_mul_f32_e64 v19, |v17|, s96
	v_exp_f32_e32 v18, v18
	v_exp_f32_e32 v19, v19
	v_min_f32_e32 v16, 0, v16
	v_min_f32_e32 v17, 0, v17
	v_add_f32_e32 v18, 1.0, v18
	v_add_f32_e32 v19, 1.0, v19
	v_log_f32_e32 v18, v18
	v_log_f32_e32 v19, v19
	s_nop 0
	v_mul_f32_e32 v20, 0x3f317217, v18
	v_mul_f32_e32 v21, 0x3f317217, v19
	v_fma_f32 v20, v18, s97, -v20
	v_fma_f32 v21, v19, s97, -v21
	v_fmac_f32_e32 v20, 0x3377d1cf, v18
	v_fmac_f32_e32 v21, 0x3377d1cf, v19
	v_fmac_f32_e32 v20, 0x3f317217, v18
	v_fmac_f32_e32 v21, 0x3f317217, v19
	v_sub_f32_e32 v16, v16, v20
	v_sub_f32_e32 v17, v17, v21
	v_mul_f32_e32 v20, 0x3d800000, v16
	v_mul_f32_e32 v21, 0x3d800000, v17
; template <bool FINAL>
; DI void gla_unit(KA a, int l, int item, LAS unsigned char* lds) {
;     ...
;         for (int jj = 0; jj < 8; ++jj) {
;             const int t = 8 * tg + jj;
;             float ga = 0.f, gb = 0.f;
;             if (t < nvalid) {
;                 const u32x4* lp = (const u32x4*)(U + (size_t)(row0 + t) * UN + U_LR);
;                 float lr[16]; unpack8(lp[0], lr); unpack8(lp[1], lr + 8);
;                 float za = bg[0], zb = bg[1];
; #pragma unroll
;                 for (int e = 0; e < 16; ++e) { za += wg[0][e] * lr[e]; zb += wg[1][e] * lr[e]; }
;                 ga = (fminf(za, 0.f) - __logf(1.f + __expf(-fabsf(za)))) * (1.f / 16.f);
;                 gb = (fminf(zb, 0.f) - __logf(1.f + __expf(-fabsf(zb)))) * (1.f / 16.f);
;             }
;             run0 += ga; run1 += gb; bl[0][jj] = run0; bl[1][jj] = run1;
.LBB0_651:
	s_and_b64 vcc, exec, s[20:21]
	v_mov_b32_e32 v43, 0
	s_cbranch_vccnz .LBB0_653
	s_add_i32 s0, s58, s51
	s_mul_hi_i32 s5, s0, 0x1600
	s_mulk_i32 s0, 0x1600
	s_add_u32 s4, s34, s0
	s_addc_u32 s5, s35, s5
	s_add_u32 s6, s4, 0x1400
	s_addc_u32 s7, s5, 0
	s_mov_b32 s96, 0xbfb8aa3b
	s_mov_b32 s97, 0x3f317217
	s_waitcnt vmcnt(0)
	v_readlane_b32 s72, v129, 8
	v_readlane_b32 s73, v129, 9
	v_readlane_b32 s74, v129, 10
	v_readlane_b32 s75, v129, 11
	v_readlane_b32 s76, v129, 12
	v_readlane_b32 s77, v129, 13
	v_readlane_b32 s78, v129, 14
	v_readlane_b32 s79, v129, 15
	s_lshl_b32 s80, s72, 16
	s_and_b32 s81, s72, 0xffff0000
	s_lshl_b32 s82, s73, 16
	s_and_b32 s83, s73, 0xffff0000
	s_lshl_b32 s84, s74, 16
	s_and_b32 s85, s74, 0xffff0000
	s_lshl_b32 s86, s75, 16
	s_and_b32 s87, s75, 0xffff0000
	s_lshl_b32 s88, s76, 16
	s_and_b32 s89, s76, 0xffff0000
	s_lshl_b32 s90, s77, 16
	s_and_b32 s91, s77, 0xffff0000
	s_lshl_b32 s92, s78, 16
	s_and_b32 s93, s78, 0xffff0000
	s_lshl_b32 s94, s79, 16
	s_and_b32 s95, s79, 0xffff0000
	v_fma_f32 v16, v118, s80, v122
	v_fma_f32 v17, v112, s80, v113
	v_fmac_f32_e32 v16, s81, v117
	v_fmac_f32_e32 v17, s81, v111
	v_fmac_f32_e32 v16, s82, v116
	v_fmac_f32_e32 v17, s82, v110
	v_fmac_f32_e32 v16, s83, v121
	v_fmac_f32_e32 v17, s83, v109
	v_fmac_f32_e32 v16, s84, v120
	v_fmac_f32_e32 v17, s84, v115
	v_fmac_f32_e32 v16, s85, v119
	v_fmac_f32_e32 v17, s85, v114
	v_fmac_f32_e32 v16, s86, v41
	v_fmac_f32_e32 v17, s86, v33
	v_fmac_f32_e32 v16, s87, v40
	v_fmac_f32_e32 v17, s87, v32
	v_fmac_f32_e32 v16, s88, v39
	v_fmac_f32_e32 v17, s88, v31
	v_fmac_f32_e32 v16, s89, v38
	v_fmac_f32_e32 v17, s89, v30
	v_fmac_f32_e32 v16, s90, v37
	v_fmac_f32_e32 v17, s90, v27
	v_fmac_f32_e32 v16, s91, v36
	v_fmac_f32_e32 v17, s91, v26
	v_fmac_f32_e32 v16, s92, v35
	v_fmac_f32_e32 v17, s92, v25
	v_fmac_f32_e32 v16, s93, v34
	v_fmac_f32_e32 v17, s93, v24
	v_fmac_f32_e32 v16, s94, v29
	v_fmac_f32_e32 v17, s94, v23
	v_fmac_f32_e32 v16, s95, v28
	v_fmac_f32_e32 v17, s95, v22
	v_mul_f32_e64 v18, |v16|, s96
	v_mul_f32_e64 v19, |v17|, s96
	v_exp_f32_e32 v18, v18
	v_exp_f32_e32 v19, v19
	v_min_f32_e32 v16, 0, v16
	v_min_f32_e32 v17, 0, v17
	v_add_f32_e32 v18, 1.0, v18
	v_add_f32_e32 v19, 1.0, v19
	v_log_f32_e32 v18, v18
	v_log_f32_e32 v19, v19
	s_nop 0
	v_mul_f32_e32 v42, 0x3f317217, v18
	v_mul_f32_e32 v43, 0x3f317217, v19
	v_fma_f32 v42, v18, s97, -v42
	v_fma_f32 v43, v19, s97, -v43
	v_fmac_f32_e32 v42, 0x3377d1cf, v18
	v_fmac_f32_e32 v43, 0x3377d1cf, v19
	v_fmac_f32_e32 v42, 0x3f317217, v18
	v_fmac_f32_e32 v43, 0x3f317217, v19
	v_sub_f32_e32 v16, v16, v42
	v_sub_f32_e32 v17, v17, v43
	v_mul_f32_e32 v42, 0x3d800000, v16
	v_mul_f32_e32 v43, 0x3d800000, v17
.LBB0_653:
	v_mov_b32_e32 v44, 0
	s_and_b64 vcc, exec, s[18:19]
	v_mov_b32_e32 v46, 0
	v_mov_b32_e32 v47, 0
	s_cbranch_vccnz .LBB0_655
	s_add_i32 s0, s57, s51
	s_mul_hi_i32 s5, s0, 0x1600
	s_mulk_i32 s0, 0x1600
	s_add_u32 s4, s34, s0
	s_addc_u32 s5, s35, s5
	s_add_u32 s6, s4, 0x1400
	s_addc_u32 s7, s5, 0
	s_mov_b32 s96, 0xbfb8aa3b
	s_mov_b32 s97, 0x3f317217
	s_waitcnt vmcnt(0)
	v_readlane_b32 s72, v129, 16
	v_readlane_b32 s73, v129, 17
	v_readlane_b32 s74, v129, 18
	v_readlane_b32 s75, v129, 19
	v_readlane_b32 s76, v129, 20
	v_readlane_b32 s77, v129, 21
	v_readlane_b32 s78, v129, 22
	v_readlane_b32 s79, v129, 23
	s_lshl_b32 s80, s72, 16
	s_and_b32 s81, s72, 0xffff0000
	s_lshl_b32 s82, s73, 16
	s_and_b32 s83, s73, 0xffff0000
	s_lshl_b32 s84, s74, 16
	s_and_b32 s85, s74, 0xffff0000
	s_lshl_b32 s86, s75, 16
	s_and_b32 s87, s75, 0xffff0000
	s_lshl_b32 s88, s76, 16
	s_and_b32 s89, s76, 0xffff0000
	s_lshl_b32 s90, s77, 16
	s_and_b32 s91, s77, 0xffff0000
	s_lshl_b32 s92, s78, 16
	s_and_b32 s93, s78, 0xffff0000
	s_lshl_b32 s94, s79, 16
	s_and_b32 s95, s79, 0xffff0000
	v_fma_f32 v16, v118, s80, v122
	v_fma_f32 v17, v112, s80, v113
	v_fmac_f32_e32 v16, s81, v117
	v_fmac_f32_e32 v17, s81, v111
	v_fmac_f32_e32 v16, s82, v116
	v_fmac_f32_e32 v17, s82, v110
	v_fmac_f32_e32 v16, s83, v121
	v_fmac_f32_e32 v17, s83, v109
	v_fmac_f32_e32 v16, s84, v120
	v_fmac_f32_e32 v17, s84, v115
	v_fmac_f32_e32 v16, s85, v119
	v_fmac_f32_e32 v17, s85, v114
	v_fmac_f32_e32 v16, s86, v41
	v_fmac_f32_e32 v17, s86, v33
	v_fmac_f32_e32 v16, s87, v40
	v_fmac_f32_e32 v17, s87, v32
	v_fmac_f32_e32 v16, s88, v39
	v_fmac_f32_e32 v17, s88, v31
	v_fmac_f32_e32 v16, s89, v38
	v_fmac_f32_e32 v17, s89, v30
	v_fmac_f32_e32 v16, s90, v37
	v_fmac_f32_e32 v17, s90, v27
	v_fmac_f32_e32 v16, s91, v36
	v_fmac_f32_e32 v17, s91, v26
	v_fmac_f32_e32 v16, s92, v35
	v_fmac_f32_e32 v17, s92, v25
	v_fmac_f32_e32 v16, s93, v34
	v_fmac_f32_e32 v17, s93, v24
	v_fmac_f32_e32 v16, s94, v29
	v_fmac_f32_e32 v17, s94, v23
	v_fmac_f32_e32 v16, s95, v28
	v_fmac_f32_e32 v17, s95, v22
	v_mul_f32_e64 v18, |v16|, s96
	v_mul_f32_e64 v19, |v17|, s96
	v_exp_f32_e32 v18, v18
	v_exp_f32_e32 v19, v19
	v_min_f32_e32 v16, 0, v16
	v_min_f32_e32 v17, 0, v17
	v_add_f32_e32 v18, 1.0, v18
	v_add_f32_e32 v19, 1.0, v19
	v_log_f32_e32 v18, v18
	v_log_f32_e32 v19, v19
	s_nop 0
	v_mul_f32_e32 v46, 0x3f317217, v18
	v_mul_f32_e32 v47, 0x3f317217, v19
	v_fma_f32 v46, v18, s97, -v46
	v_fma_f32 v47, v19, s97, -v47
	v_fmac_f32_e32 v46, 0x3377d1cf, v18
	v_fmac_f32_e32 v47, 0x3377d1cf, v19
	v_fmac_f32_e32 v46, 0x3f317217, v18
	v_fmac_f32_e32 v47, 0x3f317217, v19
	v_sub_f32_e32 v16, v16, v46
	v_sub_f32_e32 v17, v17, v47
	v_mul_f32_e32 v46, 0x3d800000, v16
	v_mul_f32_e32 v47, 0x3d800000, v17
; template <bool FINAL>
; DI void gla_unit(KA a, int l, int item, LAS unsigned char* lds) {
;     ...
;         for (int jj = 0; jj < 8; ++jj) {
;             const int t = 8 * tg + jj;
;             float ga = 0.f, gb = 0.f;
;             if (t < nvalid) {
;                 const u32x4* lp = (const u32x4*)(U + (size_t)(row0 + t) * UN + U_LR);
;                 float lr[16]; unpack8(lp[0], lr); unpack8(lp[1], lr + 8);
;                 float za = bg[0], zb = bg[1];
; #pragma unroll
;                 for (int e = 0; e < 16; ++e) { za += wg[0][e] * lr[e]; zb += wg[1][e] * lr[e]; }
;                 ga = (fminf(za, 0.f) - __logf(1.f + __expf(-fabsf(za)))) * (1.f / 16.f);
;                 gb = (fminf(zb, 0.f) - __logf(1.f + __expf(-fabsf(zb)))) * (1.f / 16.f);
;             }
;             run0 += ga; run1 += gb; bl[0][jj] = run0; bl[1][jj] = run1;
.LBB0_655:
	s_and_b64 vcc, exec, s[16:17]
	v_mov_b32_e32 v45, 0
	s_cbranch_vccnz .LBB0_657
	s_add_i32 s0, s56, s51
	s_mul_hi_i32 s5, s0, 0x1600
	s_mulk_i32 s0, 0x1600
	s_add_u32 s4, s34, s0
	s_addc_u32 s5, s35, s5
	s_add_u32 s6, s4, 0x1400
	s_addc_u32 s7, s5, 0
	s_mov_b32 s96, 0xbfb8aa3b
	s_mov_b32 s97, 0x3f317217
	s_waitcnt vmcnt(0)
	v_readlane_b32 s72, v129, 24
	v_readlane_b32 s73, v129, 25
	v_readlane_b32 s74, v129, 26
	v_readlane_b32 s75, v129, 27
	v_readlane_b32 s76, v129, 28
	v_readlane_b32 s77, v129, 29
	v_readlane_b32 s78, v129, 30
	v_readlane_b32 s79, v129, 31
	s_lshl_b32 s80, s72, 16
	s_and_b32 s81, s72, 0xffff0000
	s_lshl_b32 s82, s73, 16
	s_and_b32 s83, s73, 0xffff0000
	s_lshl_b32 s84, s74, 16
	s_and_b32 s85, s74, 0xffff0000
	s_lshl_b32 s86, s75, 16
	s_and_b32 s87, s75, 0xffff0000
	s_lshl_b32 s88, s76, 16
	s_and_b32 s89, s76, 0xffff0000
	s_lshl_b32 s90, s77, 16
	s_and_b32 s91, s77, 0xffff0000
	s_lshl_b32 s92, s78, 16
	s_and_b32 s93, s78, 0xffff0000
	s_lshl_b32 s94, s79, 16
	s_and_b32 s95, s79, 0xffff0000
	v_fma_f32 v16, v118, s80, v122
	v_fma_f32 v17, v112, s80, v113
	v_fmac_f32_e32 v16, s81, v117
	v_fmac_f32_e32 v17, s81, v111
	v_fmac_f32_e32 v16, s82, v116
	v_fmac_f32_e32 v17, s82, v110
	v_fmac_f32_e32 v16, s83, v121
	v_fmac_f32_e32 v17, s83, v109
	v_fmac_f32_e32 v16, s84, v120
	v_fmac_f32_e32 v17, s84, v115
	v_fmac_f32_e32 v16, s85, v119
	v_fmac_f32_e32 v17, s85, v114
	v_fmac_f32_e32 v16, s86, v41
	v_fmac_f32_e32 v17, s86, v33
	v_fmac_f32_e32 v16, s87, v40
	v_fmac_f32_e32 v17, s87, v32
	v_fmac_f32_e32 v16, s88, v39
	v_fmac_f32_e32 v17, s88, v31
	v_fmac_f32_e32 v16, s89, v38
	v_fmac_f32_e32 v17, s89, v30
	v_fmac_f32_e32 v16, s90, v37
	v_fmac_f32_e32 v17, s90, v27
	v_fmac_f32_e32 v16, s91, v36
	v_fmac_f32_e32 v17, s91, v26
	v_fmac_f32_e32 v16, s92, v35
	v_fmac_f32_e32 v17, s92, v25
	v_fmac_f32_e32 v16, s93, v34
	v_fmac_f32_e32 v17, s93, v24
	v_fmac_f32_e32 v16, s94, v29
	v_fmac_f32_e32 v17, s94, v23
	v_fmac_f32_e32 v16, s95, v28
	v_fmac_f32_e32 v17, s95, v22
	v_mul_f32_e64 v18, |v16|, s96
	v_mul_f32_e64 v19, |v17|, s96
	v_exp_f32_e32 v18, v18
	v_exp_f32_e32 v19, v19
	v_min_f32_e32 v16, 0, v16
	v_min_f32_e32 v17, 0, v17
	v_add_f32_e32 v18, 1.0, v18
	v_add_f32_e32 v19, 1.0, v19
	v_log_f32_e32 v18, v18
	v_log_f32_e32 v19, v19
	s_nop 0
	v_mul_f32_e32 v44, 0x3f317217, v18
	v_mul_f32_e32 v45, 0x3f317217, v19
	v_fma_f32 v44, v18, s97, -v44
	v_fma_f32 v45, v19, s97, -v45
	v_fmac_f32_e32 v44, 0x3377d1cf, v18
	v_fmac_f32_e32 v45, 0x3377d1cf, v19
	v_fmac_f32_e32 v44, 0x3f317217, v18
	v_fmac_f32_e32 v45, 0x3f317217, v19
	v_sub_f32_e32 v16, v16, v44
	v_sub_f32_e32 v17, v17, v45
	v_mul_f32_e32 v44, 0x3d800000, v16
	v_mul_f32_e32 v45, 0x3d800000, v17
.LBB0_657:
	v_mov_b32_e32 v48, 0
	s_and_b64 vcc, exec, s[14:15]
	v_mov_b32_e32 v50, 0
	v_mov_b32_e32 v51, 0
	s_cbranch_vccnz .LBB0_659
	s_add_i32 s0, s55, s51
	s_mul_hi_i32 s5, s0, 0x1600
	s_mulk_i32 s0, 0x1600
	s_add_u32 s4, s34, s0
	s_addc_u32 s5, s35, s5
	s_add_u32 s6, s4, 0x1400
	s_addc_u32 s7, s5, 0
	s_mov_b32 s96, 0xbfb8aa3b
	s_mov_b32 s97, 0x3f317217
	s_waitcnt vmcnt(0)
	v_readlane_b32 s72, v129, 32
	v_readlane_b32 s73, v129, 33
	v_readlane_b32 s74, v129, 34
	v_readlane_b32 s75, v129, 35
	v_readlane_b32 s76, v129, 36
	v_readlane_b32 s77, v129, 37
	v_readlane_b32 s78, v129, 38
	v_readlane_b32 s79, v129, 39
	s_lshl_b32 s80, s72, 16
	s_and_b32 s81, s72, 0xffff0000
	s_lshl_b32 s82, s73, 16
	s_and_b32 s83, s73, 0xffff0000
	s_lshl_b32 s84, s74, 16
	s_and_b32 s85, s74, 0xffff0000
	s_lshl_b32 s86, s75, 16
	s_and_b32 s87, s75, 0xffff0000
	s_lshl_b32 s88, s76, 16
	s_and_b32 s89, s76, 0xffff0000
	s_lshl_b32 s90, s77, 16
	s_and_b32 s91, s77, 0xffff0000
	s_lshl_b32 s92, s78, 16
	s_and_b32 s93, s78, 0xffff0000
	s_lshl_b32 s94, s79, 16
	s_and_b32 s95, s79, 0xffff0000
	v_fma_f32 v16, v118, s80, v122
	v_fma_f32 v17, v112, s80, v113
	v_fmac_f32_e32 v16, s81, v117
	v_fmac_f32_e32 v17, s81, v111
	v_fmac_f32_e32 v16, s82, v116
	v_fmac_f32_e32 v17, s82, v110
	v_fmac_f32_e32 v16, s83, v121
	v_fmac_f32_e32 v17, s83, v109
	v_fmac_f32_e32 v16, s84, v120
	v_fmac_f32_e32 v17, s84, v115
	v_fmac_f32_e32 v16, s85, v119
	v_fmac_f32_e32 v17, s85, v114
	v_fmac_f32_e32 v16, s86, v41
	v_fmac_f32_e32 v17, s86, v33
	v_fmac_f32_e32 v16, s87, v40
	v_fmac_f32_e32 v17, s87, v32
	v_fmac_f32_e32 v16, s88, v39
	v_fmac_f32_e32 v17, s88, v31
	v_fmac_f32_e32 v16, s89, v38
	v_fmac_f32_e32 v17, s89, v30
	v_fmac_f32_e32 v16, s90, v37
	v_fmac_f32_e32 v17, s90, v27
	v_fmac_f32_e32 v16, s91, v36
	v_fmac_f32_e32 v17, s91, v26
	v_fmac_f32_e32 v16, s92, v35
	v_fmac_f32_e32 v17, s92, v25
	v_fmac_f32_e32 v16, s93, v34
	v_fmac_f32_e32 v17, s93, v24
	v_fmac_f32_e32 v16, s94, v29
	v_fmac_f32_e32 v17, s94, v23
	v_fmac_f32_e32 v16, s95, v28
	v_fmac_f32_e32 v17, s95, v22
	v_mul_f32_e64 v18, |v16|, s96
	v_mul_f32_e64 v19, |v17|, s96
	v_exp_f32_e32 v18, v18
	v_exp_f32_e32 v19, v19
	v_min_f32_e32 v16, 0, v16
	v_min_f32_e32 v17, 0, v17
	v_add_f32_e32 v18, 1.0, v18
	v_add_f32_e32 v19, 1.0, v19
	v_log_f32_e32 v18, v18
	v_log_f32_e32 v19, v19
	s_nop 0
	v_mul_f32_e32 v50, 0x3f317217, v18
	v_mul_f32_e32 v51, 0x3f317217, v19
	v_fma_f32 v50, v18, s97, -v50
	v_fma_f32 v51, v19, s97, -v51
	v_fmac_f32_e32 v50, 0x3377d1cf, v18
	v_fmac_f32_e32 v51, 0x3377d1cf, v19
	v_fmac_f32_e32 v50, 0x3f317217, v18
	v_fmac_f32_e32 v51, 0x3f317217, v19
	v_sub_f32_e32 v16, v16, v50
	v_sub_f32_e32 v17, v17, v51
	v_mul_f32_e32 v50, 0x3d800000, v16
	v_mul_f32_e32 v51, 0x3d800000, v17
; template <bool FINAL>
; DI void gla_unit(KA a, int l, int item, LAS unsigned char* lds) {
;     ...
;         for (int jj = 0; jj < 8; ++jj) {
;             const int t = 8 * tg + jj;
;             float ga = 0.f, gb = 0.f;
;             if (t < nvalid) {
;                 const u32x4* lp = (const u32x4*)(U + (size_t)(row0 + t) * UN + U_LR);
;                 float lr[16]; unpack8(lp[0], lr); unpack8(lp[1], lr + 8);
;                 float za = bg[0], zb = bg[1];
; #pragma unroll
;                 for (int e = 0; e < 16; ++e) { za += wg[0][e] * lr[e]; zb += wg[1][e] * lr[e]; }
;                 ga = (fminf(za, 0.f) - __logf(1.f + __expf(-fabsf(za)))) * (1.f / 16.f);
;                 gb = (fminf(zb, 0.f) - __logf(1.f + __expf(-fabsf(zb)))) * (1.f / 16.f);
;             }
;             run0 += ga; run1 += gb; bl[0][jj] = run0; bl[1][jj] = run1;
.LBB0_659:
	s_and_b64 vcc, exec, s[12:13]
	v_mov_b32_e32 v49, 0
	s_cbranch_vccnz .LBB0_661
	s_add_i32 s0, s54, s51
	s_mul_hi_i32 s5, s0, 0x1600
	s_mulk_i32 s0, 0x1600
	s_add_u32 s4, s34, s0
	s_addc_u32 s5, s35, s5
	s_add_u32 s6, s4, 0x1400
	s_addc_u32 s7, s5, 0
	s_mov_b32 s96, 0xbfb8aa3b
	s_mov_b32 s97, 0x3f317217
	s_waitcnt vmcnt(0)
	v_readlane_b32 s72, v129, 40
	v_readlane_b32 s73, v129, 41
	v_readlane_b32 s74, v129, 42
	v_readlane_b32 s75, v129, 43
	v_readlane_b32 s76, v129, 44
	v_readlane_b32 s77, v129, 45
	v_readlane_b32 s78, v129, 46
	v_readlane_b32 s79, v129, 47
	s_lshl_b32 s80, s72, 16
	s_and_b32 s81, s72, 0xffff0000
	s_lshl_b32 s82, s73, 16
	s_and_b32 s83, s73, 0xffff0000
	s_lshl_b32 s84, s74, 16
	s_and_b32 s85, s74, 0xffff0000
	s_lshl_b32 s86, s75, 16
	s_and_b32 s87, s75, 0xffff0000
	s_lshl_b32 s88, s76, 16
	s_and_b32 s89, s76, 0xffff0000
	s_lshl_b32 s90, s77, 16
	s_and_b32 s91, s77, 0xffff0000
	s_lshl_b32 s92, s78, 16
	s_and_b32 s93, s78, 0xffff0000
	s_lshl_b32 s94, s79, 16
	s_and_b32 s95, s79, 0xffff0000
	v_fma_f32 v16, v118, s80, v122
	v_fma_f32 v17, v112, s80, v113
	v_fmac_f32_e32 v16, s81, v117
	v_fmac_f32_e32 v17, s81, v111
	v_fmac_f32_e32 v16, s82, v116
	v_fmac_f32_e32 v17, s82, v110
	v_fmac_f32_e32 v16, s83, v121
	v_fmac_f32_e32 v17, s83, v109
	v_fmac_f32_e32 v16, s84, v120
	v_fmac_f32_e32 v17, s84, v115
	v_fmac_f32_e32 v16, s85, v119
	v_fmac_f32_e32 v17, s85, v114
	v_fmac_f32_e32 v16, s86, v41
	v_fmac_f32_e32 v17, s86, v33
	v_fmac_f32_e32 v16, s87, v40
	v_fmac_f32_e32 v17, s87, v32
	v_fmac_f32_e32 v16, s88, v39
	v_fmac_f32_e32 v17, s88, v31
	v_fmac_f32_e32 v16, s89, v38
	v_fmac_f32_e32 v17, s89, v30
	v_fmac_f32_e32 v16, s90, v37
	v_fmac_f32_e32 v17, s90, v27
	v_fmac_f32_e32 v16, s91, v36
	v_fmac_f32_e32 v17, s91, v26
	v_fmac_f32_e32 v16, s92, v35
	v_fmac_f32_e32 v17, s92, v25
	v_fmac_f32_e32 v16, s93, v34
	v_fmac_f32_e32 v17, s93, v24
	v_fmac_f32_e32 v16, s94, v29
	v_fmac_f32_e32 v17, s94, v23
	v_fmac_f32_e32 v16, s95, v28
	v_fmac_f32_e32 v17, s95, v22
	v_mul_f32_e64 v18, |v16|, s96
	v_mul_f32_e64 v19, |v17|, s96
	v_exp_f32_e32 v18, v18
	v_exp_f32_e32 v19, v19
	v_min_f32_e32 v16, 0, v16
	v_min_f32_e32 v17, 0, v17
	v_add_f32_e32 v18, 1.0, v18
	v_add_f32_e32 v19, 1.0, v19
	v_log_f32_e32 v18, v18
	v_log_f32_e32 v19, v19
	s_nop 0
	v_mul_f32_e32 v48, 0x3f317217, v18
	v_mul_f32_e32 v49, 0x3f317217, v19
	v_fma_f32 v48, v18, s97, -v48
	v_fma_f32 v49, v19, s97, -v49
	v_fmac_f32_e32 v48, 0x3377d1cf, v18
	v_fmac_f32_e32 v49, 0x3377d1cf, v19
	v_fmac_f32_e32 v48, 0x3f317217, v18
	v_fmac_f32_e32 v49, 0x3f317217, v19
	v_sub_f32_e32 v16, v16, v48
	v_sub_f32_e32 v17, v17, v49
	v_mul_f32_e32 v48, 0x3d800000, v16
	v_mul_f32_e32 v49, 0x3d800000, v17
; template <bool FINAL>
; DI void gla_unit(KA a, int l, int item, LAS unsigned char* lds) {
;     ...
;         for (int jj = 0; jj < 8; ++jj) {
;             const int t = 8 * tg + jj;
;             float ga = 0.f, gb = 0.f;
;             if (t < nvalid) {
;                 const u32x4* lp = (const u32x4*)(U + (size_t)(row0 + t) * UN + U_LR);
;                 float lr[16]; unpack8(lp[0], lr); unpack8(lp[1], lr + 8);
;                 float za = bg[0], zb = bg[1];
; #pragma unroll
;                 for (int e = 0; e < 16; ++e) { za += wg[0][e] * lr[e]; zb += wg[1][e] * lr[e]; }
;                 ga = (fminf(za, 0.f) - __logf(1.f + __expf(-fabsf(za)))) * (1.f / 16.f);
;                 gb = (fminf(zb, 0.f) - __logf(1.f + __expf(-fabsf(zb)))) * (1.f / 16.f);
;             }
;             run0 += ga; run1 += gb; bl[0][jj] = run0; bl[1][jj] = run1;
.LBB0_661:
	v_mov_b32_e32 v52, 0
	s_and_b64 vcc, exec, s[10:11]
	v_mov_b32_e32 v54, 0
	v_mov_b32_e32 v55, 0
	s_cbranch_vccnz .LBB0_663
	s_add_i32 s0, s53, s51
	s_mul_hi_i32 s5, s0, 0x1600
	s_mulk_i32 s0, 0x1600
	s_add_u32 s4, s34, s0
	s_addc_u32 s5, s35, s5
	s_add_u32 s6, s4, 0x1400
	s_addc_u32 s7, s5, 0
	s_mov_b32 s96, 0xbfb8aa3b
	s_mov_b32 s97, 0x3f317217
	s_waitcnt vmcnt(0)
	v_readlane_b32 s72, v129, 48
	v_readlane_b32 s73, v129, 49
	v_readlane_b32 s74, v129, 50
	v_readlane_b32 s75, v129, 51
	v_readlane_b32 s76, v129, 52
	v_readlane_b32 s77, v129, 53
	v_readlane_b32 s78, v129, 54
	v_readlane_b32 s79, v129, 55
	s_lshl_b32 s80, s72, 16
	s_and_b32 s81, s72, 0xffff0000
	s_lshl_b32 s82, s73, 16
	s_and_b32 s83, s73, 0xffff0000
	s_lshl_b32 s84, s74, 16
	s_and_b32 s85, s74, 0xffff0000
	s_lshl_b32 s86, s75, 16
	s_and_b32 s87, s75, 0xffff0000
	s_lshl_b32 s88, s76, 16
	s_and_b32 s89, s76, 0xffff0000
	s_lshl_b32 s90, s77, 16
	s_and_b32 s91, s77, 0xffff0000
	s_lshl_b32 s92, s78, 16
	s_and_b32 s93, s78, 0xffff0000
	s_lshl_b32 s94, s79, 16
	s_and_b32 s95, s79, 0xffff0000
	v_fma_f32 v16, v118, s80, v122
	v_fma_f32 v17, v112, s80, v113
	v_fmac_f32_e32 v16, s81, v117
	v_fmac_f32_e32 v17, s81, v111
	v_fmac_f32_e32 v16, s82, v116
	v_fmac_f32_e32 v17, s82, v110
	v_fmac_f32_e32 v16, s83, v121
	v_fmac_f32_e32 v17, s83, v109
	v_fmac_f32_e32 v16, s84, v120
	v_fmac_f32_e32 v17, s84, v115
	v_fmac_f32_e32 v16, s85, v119
	v_fmac_f32_e32 v17, s85, v114
	v_fmac_f32_e32 v16, s86, v41
	v_fmac_f32_e32 v17, s86, v33
	v_fmac_f32_e32 v16, s87, v40
	v_fmac_f32_e32 v17, s87, v32
	v_fmac_f32_e32 v16, s88, v39
	v_fmac_f32_e32 v17, s88, v31
	v_fmac_f32_e32 v16, s89, v38
	v_fmac_f32_e32 v17, s89, v30
	v_fmac_f32_e32 v16, s90, v37
	v_fmac_f32_e32 v17, s90, v27
	v_fmac_f32_e32 v16, s91, v36
	v_fmac_f32_e32 v17, s91, v26
	v_fmac_f32_e32 v16, s92, v35
	v_fmac_f32_e32 v17, s92, v25
	v_fmac_f32_e32 v16, s93, v34
	v_fmac_f32_e32 v17, s93, v24
	v_fmac_f32_e32 v16, s94, v29
	v_fmac_f32_e32 v17, s94, v23
	v_fmac_f32_e32 v16, s95, v28
	v_fmac_f32_e32 v17, s95, v22
	v_mul_f32_e64 v18, |v16|, s96
	v_mul_f32_e64 v19, |v17|, s96
	v_exp_f32_e32 v18, v18
	v_exp_f32_e32 v19, v19
	v_min_f32_e32 v16, 0, v16
	v_min_f32_e32 v17, 0, v17
	v_add_f32_e32 v18, 1.0, v18
	v_add_f32_e32 v19, 1.0, v19
	v_log_f32_e32 v18, v18
	v_log_f32_e32 v19, v19
	s_nop 0
	v_mul_f32_e32 v54, 0x3f317217, v18
	v_mul_f32_e32 v55, 0x3f317217, v19
	v_fma_f32 v54, v18, s97, -v54
	v_fma_f32 v55, v19, s97, -v55
	v_fmac_f32_e32 v54, 0x3377d1cf, v18
	v_fmac_f32_e32 v55, 0x3377d1cf, v19
	v_fmac_f32_e32 v54, 0x3f317217, v18
	v_fmac_f32_e32 v55, 0x3f317217, v19
	v_sub_f32_e32 v16, v16, v54
	v_sub_f32_e32 v17, v17, v55
	v_mul_f32_e32 v54, 0x3d800000, v16
	v_mul_f32_e32 v55, 0x3d800000, v17
.LBB0_663:
	s_and_b64 vcc, exec, s[8:9]
	v_mov_b32_e32 v53, 0
	s_cbranch_vccnz .LBB0_665
	s_add_i32 s0, s52, s51
	s_mul_hi_i32 s5, s0, 0x1600
	s_mulk_i32 s0, 0x1600
	s_add_u32 s4, s34, s0
	s_addc_u32 s5, s35, s5
	s_add_u32 s6, s4, 0x1400
	s_addc_u32 s7, s5, 0
	s_mov_b32 s96, 0xbfb8aa3b
	s_mov_b32 s97, 0x3f317217
	s_waitcnt vmcnt(0)
	v_readlane_b32 s72, v129, 56
	v_readlane_b32 s73, v129, 57
	v_readlane_b32 s74, v129, 58
	v_readlane_b32 s75, v129, 59
	v_readlane_b32 s76, v129, 60
	v_readlane_b32 s77, v129, 61
	v_readlane_b32 s78, v129, 62
	v_readlane_b32 s79, v129, 63
	s_lshl_b32 s80, s72, 16
	s_and_b32 s81, s72, 0xffff0000
	s_lshl_b32 s82, s73, 16
	s_and_b32 s83, s73, 0xffff0000
	s_lshl_b32 s84, s74, 16
	s_and_b32 s85, s74, 0xffff0000
	s_lshl_b32 s86, s75, 16
	s_and_b32 s87, s75, 0xffff0000
	s_lshl_b32 s88, s76, 16
	s_and_b32 s89, s76, 0xffff0000
	s_lshl_b32 s90, s77, 16
	s_and_b32 s91, s77, 0xffff0000
	s_lshl_b32 s92, s78, 16
	s_and_b32 s93, s78, 0xffff0000
	s_lshl_b32 s94, s79, 16
	s_and_b32 s95, s79, 0xffff0000
	v_fma_f32 v16, v118, s80, v122
	v_fma_f32 v17, v112, s80, v113
	v_fmac_f32_e32 v16, s81, v117
	v_fmac_f32_e32 v17, s81, v111
	v_fmac_f32_e32 v16, s82, v116
	v_fmac_f32_e32 v17, s82, v110
	v_fmac_f32_e32 v16, s83, v121
	v_fmac_f32_e32 v17, s83, v109
	v_fmac_f32_e32 v16, s84, v120
	v_fmac_f32_e32 v17, s84, v115
	v_fmac_f32_e32 v16, s85, v119
	v_fmac_f32_e32 v17, s85, v114
	v_fmac_f32_e32 v16, s86, v41
	v_fmac_f32_e32 v17, s86, v33
	v_fmac_f32_e32 v16, s87, v40
	v_fmac_f32_e32 v17, s87, v32
	v_fmac_f32_e32 v16, s88, v39
	v_fmac_f32_e32 v17, s88, v31
	v_fmac_f32_e32 v16, s89, v38
	v_fmac_f32_e32 v17, s89, v30
	v_fmac_f32_e32 v16, s90, v37
	v_fmac_f32_e32 v17, s90, v27
	v_fmac_f32_e32 v16, s91, v36
	v_fmac_f32_e32 v17, s91, v26
	v_fmac_f32_e32 v16, s92, v35
	v_fmac_f32_e32 v17, s92, v25
	v_fmac_f32_e32 v16, s93, v34
	v_fmac_f32_e32 v17, s93, v24
	v_fmac_f32_e32 v16, s94, v29
	v_fmac_f32_e32 v17, s94, v23
	v_fmac_f32_e32 v16, s95, v28
	v_fmac_f32_e32 v17, s95, v22
	v_mul_f32_e64 v18, |v16|, s96
	v_mul_f32_e64 v19, |v17|, s96
	v_exp_f32_e32 v18, v18
	v_exp_f32_e32 v19, v19
	v_min_f32_e32 v16, 0, v16
	v_min_f32_e32 v17, 0, v17
	v_add_f32_e32 v18, 1.0, v18
	v_add_f32_e32 v19, 1.0, v19
	v_log_f32_e32 v18, v18
	v_log_f32_e32 v19, v19
	s_nop 0
	v_mul_f32_e32 v52, 0x3f317217, v18
	v_mul_f32_e32 v53, 0x3f317217, v19
	v_fma_f32 v52, v18, s97, -v52
	v_fma_f32 v53, v19, s97, -v53
	v_fmac_f32_e32 v52, 0x3377d1cf, v18
	v_fmac_f32_e32 v53, 0x3377d1cf, v19
	v_fmac_f32_e32 v52, 0x3f317217, v18
	v_fmac_f32_e32 v53, 0x3f317217, v19
	v_sub_f32_e32 v16, v16, v52
	v_sub_f32_e32 v17, v17, v53
	v_mul_f32_e32 v52, 0x3d800000, v16
	v_mul_f32_e32 v53, 0x3d800000, v17

; #define LBAR() do { asm volatile("s_waitcnt lgkmcnt(0)" ::: "memory"); __builtin_amdgcn_s_barrier(); asm volatile("" ::: "memory"); } while (0)
; DI KA get_ka() { KA p = (KA)__builtin_amdgcn_kernarg_segment_ptr(); asm volatile("" : "+s"(p)); return p; }
; __global__ void __launch_bounds__(512, 2) hymba_fwd(Args a_unused) {
;     ...
;         for (int it = blockIdx.x; it < NUNIT + 2 * NUNIT; it += gridDim.x) {
;             if (it < NUNIT) { lru_unit<true>(get_ka(), l, it, lds); LBAR(); }
;             else { for (int rep = 0; rep < REP_M3G; ++rep) gla_unit<true>(get_ka(), l, it - NUNIT, lds); }
;         }
.LBB0_791:
	v_readlane_b32 s2, v254, 0
	s_cmpk_lt_i32 s62, 0x188
	s_cbranch_scc0 .Lm3_adv_gla
	s_add_i32 s3, s62, 0x100
	s_cmp_eq_u32 s62, s2
	s_cselect_b32 s4, 1, 0
	s_cmpk_lt_i32 s3, 0x188
	s_cselect_b32 s5, 1, 0
	s_and_b32 s4, s4, s5
	s_cmp_lg_u32 s4, 0
	s_cbranch_scc0 .Lm3_first_gla
	s_mov_b32 s62, s3
	s_branch .LBB0_792
.Lm3_first_gla:
	s_cmpk_lt_i32 s2, 0x88
	s_cselect_b32 s3, 0, 0x88
	s_add_i32 s62, s2, s3
	s_addk_i32 s62, 0x188
	s_branch .LBB0_792
.Lm3_adv_gla:
	s_sub_i32 s3, s62, 0x188
	s_cmpk_lt_i32 s2, 0x88
	s_cbranch_scc0 .Lm3_adv_light
	s_cmpk_lt_i32 s3, 0x88
	s_cbranch_scc0 .LBB0_1057
	s_addk_i32 s62, 0x88
	s_branch .LBB0_792
.Lm3_adv_light:
	s_sub_i32 s4, s3, 0x110
	s_cmpk_lt_i32 s4, 0x168
	s_cbranch_scc0 .Lm3_adv_light5
	s_addk_i32 s62, 0x78
	s_branch .LBB0_792
.Lm3_adv_light5:
	s_cmpk_lt_i32 s4, 0x1e0
	s_cbranch_scc0 .LBB0_1057
	s_sub_i32 s5, s2, 0x88
	s_cmpk_lt_i32 s5, 32
	s_cbranch_scc0 .LBB0_1057
	s_add_i32 s62, s5, 0x478
	s_branch .LBB0_792

; DI int crow(int reg, int h) { return (reg & 3) + 8 * (reg >> 2) + 4 * h; }
; template <bool FINAL>
; DI void gla_unit(KA a, int l, int item, LAS unsigned char* lds) {
;     ...
;     if (FINAL) {
; #pragma unroll
;         for (int q = 0; q < 4; ++q) gnv[q] = *(const f32x4*)(a->in[20] + l * DV + vdvc + 4 * q);
;     }
;     float s0v[2][16];
;     if (!FINAL && !u.prompt) {
; #pragma unroll
;         for (int hh = 0; hh < 2; ++hh)
; #pragma unroll
;             for (int i = 0; i < 16; ++i) s0v[hh][i] = __builtin_nontemporal_load(S0[hh] + (32 * (w >> 2) + crow(i, h)) * 128 + 32 * (w & 3) + r);
;     }
;     float bl[2][8];
;     {
;         float wg[2][16], bg[2];
; #pragma unroll
;         for (int hh = 0; hh < 2; ++hh) {
;             const float* wg2 = a->in[18] + (size_t)l * 16 * 256 + (2 * hp + hh) * 64 + dk;
; #pragma unroll
;             for (int e = 0; e < 16; ++e) wg[hh][e] = wg2[e * 256];
;             bg[hh] = a->in[19][l * 256 + (2 * hp + hh) * 64 + dk];
;         }
;         float run0 = 0.f, run1 = 0.f;
; #pragma unroll
;         for (int jj = 0; jj < 8; ++jj) {
;             const int t = 8 * tg + jj;
;             float ga = 0.f, gb = 0.f;
;             if (t < nvalid) {
;                 const u32x4* lp = (const u32x4*)(U + (size_t)(row0 + t) * UN + U_LR);
;                 float lr[16]; unpack8(lp[0], lr); unpack8(lp[1], lr + 8);
;                 float za = bg[0], zb = bg[1];
; #pragma unroll
;                 for (int e = 0; e < 16; ++e) { za += wg[0][e] * lr[e]; zb += wg[1][e] * lr[e]; }
;                 ga = (fminf(za, 0.f) - __logf(1.f + __expf(-fabsf(za)))) * (1.f / 16.f);
;                 gb = (fminf(zb, 0.f) - __logf(1.f + __expf(-fabsf(zb)))) * (1.f / 16.f);
;             }
;             run0 += ga; run1 += gb; bl[0][jj] = run0; bl[1][jj] = run1;
.LBB0_885:
	s_load_dwordx4 s[4:7], s[2:3], 0x90
	s_nop 0
	s_load_dwordx2 s[2:3], s[2:3], 0xa0
	s_lshl_b64 s[26:27], s[60:61], 2
	v_lshlrev_b32_e32 v124, 2, v167
	v_lshlrev_b32_e32 v80, 2, v85
	v_mov_b32_e32 v81, v145
	s_waitcnt lgkmcnt(0)
	s_add_u32 s2, s2, s26
	s_addc_u32 s3, s3, s27
	global_load_dwordx4 v[32:35], v124, s[2:3] offset:48
	global_load_dwordx4 v[52:55], v124, s[2:3] offset:32
	global_load_dwordx4 v[56:59], v124, s[2:3] offset:16
	global_load_dwordx4 v[60:63], v124, s[2:3]
	v_readlane_b32 s2, v255, 1
	v_readlane_b32 s3, v255, 2
	s_lshl_b64 s[2:3], s[2:3], 2
	s_add_u32 s2, s4, s2
	s_addc_u32 s3, s5, s3
	v_readlane_b32 s0, v255, 3
	v_lshl_add_u64 v[80:81], s[2:3], 0, v[80:81]
	v_mov_b32_e32 v95, v145
	v_or_b32_e32 v110, s0, v85
	s_lshl_b32 s0, s54, 2
	v_lshl_add_u64 v[80:81], v[80:81], 0, s[0:1]
	s_movk_i32 s0, 0x1000
	v_add_co_u32_e32 v82, vcc, s0, v80
	s_movk_i32 s0, 0x2000
	s_nop 0
	v_addc_co_u32_e32 v83, vcc, 0, v81, vcc
	v_add_co_u32_e32 v86, vcc, s0, v80
	s_movk_i32 s0, 0x3000
	s_nop 0
	v_addc_co_u32_e32 v87, vcc, 0, v81, vcc
	v_add_co_u32_e32 v108, vcc, s0, v80
	v_or_b32_e32 v94, s54, v110
	s_nop 0
	v_addc_co_u32_e32 v109, vcc, 0, v81, vcc
	v_lshl_add_u64 v[94:95], v[94:95], 2, s[6:7]
	global_load_dword v176, v[80:81], off
	global_load_dword v175, v[80:81], off offset:1024
	global_load_dword v174, v[80:81], off offset:2048
	global_load_dword v173, v[80:81], off offset:3072
	global_load_dword v179, v[86:87], off offset:-4096
	global_load_dword v178, v[82:83], off offset:1024
	global_load_dword v99, v[82:83], off offset:2048
	global_load_dword v98, v[82:83], off offset:3072
	global_load_dword v97, v[86:87], off
	global_load_dword v96, v[86:87], off offset:1024
	global_load_dword v93, v[86:87], off offset:2048
	global_load_dword v92, v[86:87], off offset:3072
	global_load_dword v91, v[108:109], off
	global_load_dword v90, v[108:109], off offset:1024
	global_load_dword v89, v[108:109], off offset:2048
	global_load_dword v88, v[108:109], off offset:3072
	global_load_dword v177, v[94:95], off
	global_load_dword v182, v[80:81], off offset:256
	global_load_dword v181, v[80:81], off offset:1280
	global_load_dword v180, v[80:81], off offset:2304
	global_load_dword v185, v[80:81], off offset:3328
	global_load_dword v184, v[82:83], off offset:256
	global_load_dword v183, v[82:83], off offset:1280
	global_load_dword v107, v[82:83], off offset:2304
	global_load_dword v106, v[82:83], off offset:3328
	global_load_dword v105, v[86:87], off offset:256
	global_load_dword v104, v[86:87], off offset:1280
	global_load_dword v103, v[86:87], off offset:2304
	global_load_dword v102, v[86:87], off offset:3328
	global_load_dword v101, v[108:109], off offset:256
	global_load_dword v100, v[108:109], off offset:1280
	global_load_dword v95, v[108:109], off offset:2304
	global_load_dword v94, v[108:109], off offset:3328
	v_add_u32_e32 v80, s54, v110
	v_mov_b32_e32 v81, v145
	v_lshl_add_u64 v[80:81], v[80:81], 2, s[6:7]
	global_load_dword v186, v[80:81], off offset:256
	v_lshrrev_b32_e32 v192, 3, v85
	v_mul_u32_u24_e32 v192, 0x1600, v192
	v_and_b32_e32 v193, 7, v85
	v_lshl_add_u32 v192, v193, 2, v192
	s_add_i32 s72, s53, s46
	s_mul_hi_i32 s73, s72, 0x1600
	s_mulk_i32 s72, 0x1600
	s_add_u32 s72, s30, s72
	s_addc_u32 s73, s31, s73
	s_add_u32 s72, s72, 0x1400
	s_addc_u32 s73, s73, 0
	global_load_dword v193, v192, s[72:73]
	v_mov_b32_e32 v108, 0
	s_and_b64 vcc, exec, s[24:25]
	v_mov_b32_e32 v86, 0
	v_mov_b32_e32 v87, 0
	s_cbranch_vccnz .LBB0_887
	s_add_i32 s0, s53, s46
	s_mul_hi_i32 s3, s0, 0x1600
	s_mulk_i32 s0, 0x1600
	s_add_u32 s2, s30, s0
	s_addc_u32 s3, s31, s3
	s_add_u32 s4, s2, 0x1400
	s_addc_u32 s5, s3, 0
	s_mov_b32 s96, 0xbfb8aa3b
	s_mov_b32 s97, 0x3f317217
	s_waitcnt vmcnt(0)
	v_readlane_b32 s72, v193, 0
	v_readlane_b32 s73, v193, 1
	v_readlane_b32 s74, v193, 2
	v_readlane_b32 s75, v193, 3
	v_readlane_b32 s76, v193, 4
	v_readlane_b32 s77, v193, 5
	v_readlane_b32 s78, v193, 6
	v_readlane_b32 s79, v193, 7
	s_lshl_b32 s80, s72, 16
	s_and_b32 s81, s72, 0xffff0000
	s_lshl_b32 s82, s73, 16
	s_and_b32 s83, s73, 0xffff0000
	s_lshl_b32 s84, s74, 16
	s_and_b32 s85, s74, 0xffff0000
	s_lshl_b32 s86, s75, 16
	s_and_b32 s87, s75, 0xffff0000
	s_lshl_b32 s88, s76, 16
	s_and_b32 s89, s76, 0xffff0000
	s_lshl_b32 s90, s77, 16
	s_and_b32 s91, s77, 0xffff0000
	s_lshl_b32 s92, s78, 16
	s_and_b32 s93, s78, 0xffff0000
	s_lshl_b32 s94, s79, 16
	s_and_b32 s95, s79, 0xffff0000
	v_fma_f32 v80, v176, s80, v177
	v_fma_f32 v81, v182, s80, v186
	v_fmac_f32_e32 v80, s81, v175
	v_fmac_f32_e32 v81, s81, v181
	v_fmac_f32_e32 v80, s82, v174
	v_fmac_f32_e32 v81, s82, v180
	v_fmac_f32_e32 v80, s83, v173
	v_fmac_f32_e32 v81, s83, v185
	v_fmac_f32_e32 v80, s84, v179
	v_fmac_f32_e32 v81, s84, v184
	v_fmac_f32_e32 v80, s85, v178
	v_fmac_f32_e32 v81, s85, v183
	v_fmac_f32_e32 v80, s86, v99
	v_fmac_f32_e32 v81, s86, v107
	v_fmac_f32_e32 v80, s87, v98
	v_fmac_f32_e32 v81, s87, v106
	v_fmac_f32_e32 v80, s88, v97
	v_fmac_f32_e32 v81, s88, v105
	v_fmac_f32_e32 v80, s89, v96
	v_fmac_f32_e32 v81, s89, v104
	v_fmac_f32_e32 v80, s90, v93
	v_fmac_f32_e32 v81, s90, v103
	v_fmac_f32_e32 v80, s91, v92
	v_fmac_f32_e32 v81, s91, v102
	v_fmac_f32_e32 v80, s92, v91
	v_fmac_f32_e32 v81, s92, v101
	v_fmac_f32_e32 v80, s93, v90
	v_fmac_f32_e32 v81, s93, v100
	v_fmac_f32_e32 v80, s94, v89
	v_fmac_f32_e32 v81, s94, v95
	v_fmac_f32_e32 v80, s95, v88
	v_fmac_f32_e32 v81, s95, v94
	v_mul_f32_e64 v82, |v80|, s96
	v_mul_f32_e64 v83, |v81|, s96
	v_exp_f32_e32 v82, v82
	v_exp_f32_e32 v83, v83
	v_min_f32_e32 v80, 0, v80
	v_min_f32_e32 v81, 0, v81
	v_add_f32_e32 v82, 1.0, v82
	v_add_f32_e32 v83, 1.0, v83
	v_log_f32_e32 v82, v82
	v_log_f32_e32 v83, v83
	s_nop 0
	v_mul_f32_e32 v86, 0x3f317217, v82
	v_mul_f32_e32 v87, 0x3f317217, v83
	v_fma_f32 v86, v82, s97, -v86
	v_fma_f32 v87, v83, s97, -v87
	v_fmac_f32_e32 v86, 0x3377d1cf, v82
	v_fmac_f32_e32 v87, 0x3377d1cf, v83
	v_fmac_f32_e32 v86, 0x3f317217, v82
	v_fmac_f32_e32 v87, 0x3f317217, v83
	v_sub_f32_e32 v80, v80, v86
	v_sub_f32_e32 v81, v81, v87
	v_mul_f32_e32 v86, 0x3d800000, v80
	v_mul_f32_e32 v87, 0x3d800000, v81
; template <bool FINAL>
; DI void gla_unit(KA a, int l, int item, LAS unsigned char* lds) {
;     ...
;         for (int jj = 0; jj < 8; ++jj) {
;             const int t = 8 * tg + jj;
;             float ga = 0.f, gb = 0.f;
;             if (t < nvalid) {
;                 const u32x4* lp = (const u32x4*)(U + (size_t)(row0 + t) * UN + U_LR);
;                 float lr[16]; unpack8(lp[0], lr); unpack8(lp[1], lr + 8);
;                 float za = bg[0], zb = bg[1];
; #pragma unroll
;                 for (int e = 0; e < 16; ++e) { za += wg[0][e] * lr[e]; zb += wg[1][e] * lr[e]; }
;                 ga = (fminf(za, 0.f) - __logf(1.f + __expf(-fabsf(za)))) * (1.f / 16.f);
;                 gb = (fminf(zb, 0.f) - __logf(1.f + __expf(-fabsf(zb)))) * (1.f / 16.f);
;             }
;             run0 += ga; run1 += gb; bl[0][jj] = run0; bl[1][jj] = run1;
.LBB0_887:
	s_and_b64 vcc, exec, s[22:23]
	v_mov_b32_e32 v109, 0
	s_cbranch_vccnz .LBB0_889
	s_add_i32 s0, s45, s46
	s_mul_hi_i32 s3, s0, 0x1600
	s_mulk_i32 s0, 0x1600
	s_add_u32 s2, s30, s0
	s_addc_u32 s3, s31, s3
	s_add_u32 s4, s2, 0x1400
	s_addc_u32 s5, s3, 0
	s_mov_b32 s96, 0xbfb8aa3b
	s_mov_b32 s97, 0x3f317217
	s_waitcnt vmcnt(0)
	v_readlane_b32 s72, v193, 8
	v_readlane_b32 s73, v193, 9
	v_readlane_b32 s74, v193, 10
	v_readlane_b32 s75, v193, 11
	v_readlane_b32 s76, v193, 12
	v_readlane_b32 s77, v193, 13
	v_readlane_b32 s78, v193, 14
	v_readlane_b32 s79, v193, 15
	s_lshl_b32 s80, s72, 16
	s_and_b32 s81, s72, 0xffff0000
	s_lshl_b32 s82, s73, 16
	s_and_b32 s83, s73, 0xffff0000
	s_lshl_b32 s84, s74, 16
	s_and_b32 s85, s74, 0xffff0000
	s_lshl_b32 s86, s75, 16
	s_and_b32 s87, s75, 0xffff0000
	s_lshl_b32 s88, s76, 16
	s_and_b32 s89, s76, 0xffff0000
	s_lshl_b32 s90, s77, 16
	s_and_b32 s91, s77, 0xffff0000
	s_lshl_b32 s92, s78, 16
	s_and_b32 s93, s78, 0xffff0000
	s_lshl_b32 s94, s79, 16
	s_and_b32 s95, s79, 0xffff0000
	v_fma_f32 v80, v182, s80, v186
	v_fma_f32 v81, v176, s80, v177
	v_fmac_f32_e32 v80, s81, v181
	v_fmac_f32_e32 v81, s81, v175
	v_fmac_f32_e32 v80, s82, v180
	v_fmac_f32_e32 v81, s82, v174
	v_fmac_f32_e32 v80, s83, v185
	v_fmac_f32_e32 v81, s83, v173
	v_fmac_f32_e32 v80, s84, v184
	v_fmac_f32_e32 v81, s84, v179
	v_fmac_f32_e32 v80, s85, v183
	v_fmac_f32_e32 v81, s85, v178
	v_fmac_f32_e32 v80, s86, v107
	v_fmac_f32_e32 v81, s86, v99
	v_fmac_f32_e32 v80, s87, v106
	v_fmac_f32_e32 v81, s87, v98
	v_fmac_f32_e32 v80, s88, v105
	v_fmac_f32_e32 v81, s88, v97
	v_fmac_f32_e32 v80, s89, v104
	v_fmac_f32_e32 v81, s89, v96
	v_fmac_f32_e32 v80, s90, v103
	v_fmac_f32_e32 v81, s90, v93
	v_fmac_f32_e32 v80, s91, v102
	v_fmac_f32_e32 v81, s91, v92
	v_fmac_f32_e32 v80, s92, v101
	v_fmac_f32_e32 v81, s92, v91
	v_fmac_f32_e32 v80, s93, v100
	v_fmac_f32_e32 v81, s93, v90
	v_fmac_f32_e32 v80, s94, v95
	v_fmac_f32_e32 v81, s94, v89
	v_fmac_f32_e32 v80, s95, v94
	v_fmac_f32_e32 v81, s95, v88
	v_mul_f32_e64 v82, |v80|, s96
	v_mul_f32_e64 v83, |v81|, s96
	v_exp_f32_e32 v82, v82
	v_exp_f32_e32 v83, v83
	v_min_f32_e32 v80, 0, v80
	v_min_f32_e32 v81, 0, v81
	v_add_f32_e32 v82, 1.0, v82
	v_add_f32_e32 v83, 1.0, v83
	v_log_f32_e32 v82, v82
	v_log_f32_e32 v83, v83
	s_nop 0
	v_mul_f32_e32 v108, 0x3f317217, v82
	v_mul_f32_e32 v109, 0x3f317217, v83
	v_fma_f32 v108, v82, s97, -v108
	v_fma_f32 v109, v83, s97, -v109
	v_fmac_f32_e32 v108, 0x3377d1cf, v82
	v_fmac_f32_e32 v109, 0x3377d1cf, v83
	v_fmac_f32_e32 v108, 0x3f317217, v82
	v_fmac_f32_e32 v109, 0x3f317217, v83
	v_sub_f32_e32 v80, v80, v108
	v_sub_f32_e32 v81, v81, v109
	v_mul_f32_e32 v108, 0x3d800000, v80
	v_mul_f32_e32 v109, 0x3d800000, v81
.LBB0_889:
	v_mov_b32_e32 v110, 0
	s_and_b64 vcc, exec, s[20:21]
	v_mov_b32_e32 v112, 0
	v_mov_b32_e32 v113, 0
	s_cbranch_vccnz .LBB0_891
	s_add_i32 s0, s52, s46
	s_mul_hi_i32 s3, s0, 0x1600
	s_mulk_i32 s0, 0x1600
	s_add_u32 s2, s30, s0
	s_addc_u32 s3, s31, s3
	s_add_u32 s4, s2, 0x1400
	s_addc_u32 s5, s3, 0
	s_mov_b32 s96, 0xbfb8aa3b
	s_mov_b32 s97, 0x3f317217
	s_waitcnt vmcnt(0)
	v_readlane_b32 s72, v193, 16
	v_readlane_b32 s73, v193, 17
	v_readlane_b32 s74, v193, 18
	v_readlane_b32 s75, v193, 19
	v_readlane_b32 s76, v193, 20
	v_readlane_b32 s77, v193, 21
	v_readlane_b32 s78, v193, 22
	v_readlane_b32 s79, v193, 23
	s_lshl_b32 s80, s72, 16
	s_and_b32 s81, s72, 0xffff0000
	s_lshl_b32 s82, s73, 16
	s_and_b32 s83, s73, 0xffff0000
	s_lshl_b32 s84, s74, 16
	s_and_b32 s85, s74, 0xffff0000
	s_lshl_b32 s86, s75, 16
	s_and_b32 s87, s75, 0xffff0000
	s_lshl_b32 s88, s76, 16
	s_and_b32 s89, s76, 0xffff0000
	s_lshl_b32 s90, s77, 16
	s_and_b32 s91, s77, 0xffff0000
	s_lshl_b32 s92, s78, 16
	s_and_b32 s93, s78, 0xffff0000
	s_lshl_b32 s94, s79, 16
	s_and_b32 s95, s79, 0xffff0000
	v_fma_f32 v80, v182, s80, v186
	v_fma_f32 v81, v176, s80, v177
	v_fmac_f32_e32 v80, s81, v181
	v_fmac_f32_e32 v81, s81, v175
	v_fmac_f32_e32 v80, s82, v180
	v_fmac_f32_e32 v81, s82, v174
	v_fmac_f32_e32 v80, s83, v185
	v_fmac_f32_e32 v81, s83, v173
	v_fmac_f32_e32 v80, s84, v184
	v_fmac_f32_e32 v81, s84, v179
	v_fmac_f32_e32 v80, s85, v183
	v_fmac_f32_e32 v81, s85, v178
	v_fmac_f32_e32 v80, s86, v107
	v_fmac_f32_e32 v81, s86, v99
	v_fmac_f32_e32 v80, s87, v106
	v_fmac_f32_e32 v81, s87, v98
	v_fmac_f32_e32 v80, s88, v105
	v_fmac_f32_e32 v81, s88, v97
	v_fmac_f32_e32 v80, s89, v104
	v_fmac_f32_e32 v81, s89, v96
	v_fmac_f32_e32 v80, s90, v103
	v_fmac_f32_e32 v81, s90, v93
	v_fmac_f32_e32 v80, s91, v102
	v_fmac_f32_e32 v81, s91, v92
	v_fmac_f32_e32 v80, s92, v101
	v_fmac_f32_e32 v81, s92, v91
	v_fmac_f32_e32 v80, s93, v100
	v_fmac_f32_e32 v81, s93, v90
	v_fmac_f32_e32 v80, s94, v95
	v_fmac_f32_e32 v81, s94, v89
	v_fmac_f32_e32 v80, s95, v94
	v_fmac_f32_e32 v81, s95, v88
	v_mul_f32_e64 v82, |v80|, s96
	v_mul_f32_e64 v83, |v81|, s96
	v_exp_f32_e32 v82, v82
	v_exp_f32_e32 v83, v83
	v_min_f32_e32 v80, 0, v80
	v_min_f32_e32 v81, 0, v81
	v_add_f32_e32 v82, 1.0, v82
	v_add_f32_e32 v83, 1.0, v83
	v_log_f32_e32 v82, v82
	v_log_f32_e32 v83, v83
	s_nop 0
	v_mul_f32_e32 v112, 0x3f317217, v82
	v_mul_f32_e32 v113, 0x3f317217, v83
	v_fma_f32 v112, v82, s97, -v112
	v_fma_f32 v113, v83, s97, -v113
	v_fmac_f32_e32 v112, 0x3377d1cf, v82
	v_fmac_f32_e32 v113, 0x3377d1cf, v83
	v_fmac_f32_e32 v112, 0x3f317217, v82
	v_fmac_f32_e32 v113, 0x3f317217, v83
	v_sub_f32_e32 v80, v80, v112
	v_sub_f32_e32 v81, v81, v113
	v_mul_f32_e32 v112, 0x3d800000, v80
	v_mul_f32_e32 v113, 0x3d800000, v81
; template <bool FINAL>
; DI void gla_unit(KA a, int l, int item, LAS unsigned char* lds) {
;     ...
;         for (int jj = 0; jj < 8; ++jj) {
;             const int t = 8 * tg + jj;
;             float ga = 0.f, gb = 0.f;
;             if (t < nvalid) {
;                 const u32x4* lp = (const u32x4*)(U + (size_t)(row0 + t) * UN + U_LR);
;                 float lr[16]; unpack8(lp[0], lr); unpack8(lp[1], lr + 8);
;                 float za = bg[0], zb = bg[1];
; #pragma unroll
;                 for (int e = 0; e < 16; ++e) { za += wg[0][e] * lr[e]; zb += wg[1][e] * lr[e]; }
;                 ga = (fminf(za, 0.f) - __logf(1.f + __expf(-fabsf(za)))) * (1.f / 16.f);
;                 gb = (fminf(zb, 0.f) - __logf(1.f + __expf(-fabsf(zb)))) * (1.f / 16.f);
;             }
;             run0 += ga; run1 += gb; bl[0][jj] = run0; bl[1][jj] = run1;
.LBB0_891:
	s_and_b64 vcc, exec, s[18:19]
	v_mov_b32_e32 v111, 0
	s_cbranch_vccnz .LBB0_893
	s_add_i32 s0, s51, s46
	s_mul_hi_i32 s3, s0, 0x1600
	s_mulk_i32 s0, 0x1600
	s_add_u32 s2, s30, s0
	s_addc_u32 s3, s31, s3
	s_add_u32 s4, s2, 0x1400
	s_addc_u32 s5, s3, 0
	s_mov_b32 s96, 0xbfb8aa3b
	s_mov_b32 s97, 0x3f317217
	s_waitcnt vmcnt(0)
	v_readlane_b32 s72, v193, 24
	v_readlane_b32 s73, v193, 25
	v_readlane_b32 s74, v193, 26
	v_readlane_b32 s75, v193, 27
	v_readlane_b32 s76, v193, 28
	v_readlane_b32 s77, v193, 29
	v_readlane_b32 s78, v193, 30
	v_readlane_b32 s79, v193, 31
	s_lshl_b32 s80, s72, 16
	s_and_b32 s81, s72, 0xffff0000
	s_lshl_b32 s82, s73, 16
	s_and_b32 s83, s73, 0xffff0000
	s_lshl_b32 s84, s74, 16
	s_and_b32 s85, s74, 0xffff0000
	s_lshl_b32 s86, s75, 16
	s_and_b32 s87, s75, 0xffff0000
	s_lshl_b32 s88, s76, 16
	s_and_b32 s89, s76, 0xffff0000
	s_lshl_b32 s90, s77, 16
	s_and_b32 s91, s77, 0xffff0000
	s_lshl_b32 s92, s78, 16
	s_and_b32 s93, s78, 0xffff0000
	s_lshl_b32 s94, s79, 16
	s_and_b32 s95, s79, 0xffff0000
	v_fma_f32 v80, v182, s80, v186
	v_fma_f32 v81, v176, s80, v177
	v_fmac_f32_e32 v80, s81, v181
	v_fmac_f32_e32 v81, s81, v175
	v_fmac_f32_e32 v80, s82, v180
	v_fmac_f32_e32 v81, s82, v174
	v_fmac_f32_e32 v80, s83, v185
	v_fmac_f32_e32 v81, s83, v173
	v_fmac_f32_e32 v80, s84, v184
	v_fmac_f32_e32 v81, s84, v179
	v_fmac_f32_e32 v80, s85, v183
	v_fmac_f32_e32 v81, s85, v178
	v_fmac_f32_e32 v80, s86, v107
	v_fmac_f32_e32 v81, s86, v99
	v_fmac_f32_e32 v80, s87, v106
	v_fmac_f32_e32 v81, s87, v98
	v_fmac_f32_e32 v80, s88, v105
	v_fmac_f32_e32 v81, s88, v97
	v_fmac_f32_e32 v80, s89, v104
	v_fmac_f32_e32 v81, s89, v96
	v_fmac_f32_e32 v80, s90, v103
	v_fmac_f32_e32 v81, s90, v93
	v_fmac_f32_e32 v80, s91, v102
	v_fmac_f32_e32 v81, s91, v92
	v_fmac_f32_e32 v80, s92, v101
	v_fmac_f32_e32 v81, s92, v91
	v_fmac_f32_e32 v80, s93, v100
	v_fmac_f32_e32 v81, s93, v90
	v_fmac_f32_e32 v80, s94, v95
	v_fmac_f32_e32 v81, s94, v89
	v_fmac_f32_e32 v80, s95, v94
	v_fmac_f32_e32 v81, s95, v88
	v_mul_f32_e64 v82, |v80|, s96
	v_mul_f32_e64 v83, |v81|, s96
	v_exp_f32_e32 v82, v82
	v_exp_f32_e32 v83, v83
	v_min_f32_e32 v80, 0, v80
	v_min_f32_e32 v81, 0, v81
	v_add_f32_e32 v82, 1.0, v82
	v_add_f32_e32 v83, 1.0, v83
	v_log_f32_e32 v82, v82
	v_log_f32_e32 v83, v83
	s_nop 0
	v_mul_f32_e32 v110, 0x3f317217, v82
	v_mul_f32_e32 v111, 0x3f317217, v83
	v_fma_f32 v110, v82, s97, -v110
	v_fma_f32 v111, v83, s97, -v111
	v_fmac_f32_e32 v110, 0x3377d1cf, v82
	v_fmac_f32_e32 v111, 0x3377d1cf, v83
	v_fmac_f32_e32 v110, 0x3f317217, v82
	v_fmac_f32_e32 v111, 0x3f317217, v83
	v_sub_f32_e32 v80, v80, v110
	v_sub_f32_e32 v81, v81, v111
	v_mul_f32_e32 v110, 0x3d800000, v80
	v_mul_f32_e32 v111, 0x3d800000, v81
.LBB0_893:
	v_mov_b32_e32 v114, 0
	s_and_b64 vcc, exec, s[16:17]
	v_mov_b32_e32 v116, 0
	v_mov_b32_e32 v117, 0
	s_cbranch_vccnz .LBB0_895
	s_add_i32 s0, s50, s46
	s_mul_hi_i32 s3, s0, 0x1600
	s_mulk_i32 s0, 0x1600
	s_add_u32 s2, s30, s0
	s_addc_u32 s3, s31, s3
	s_add_u32 s4, s2, 0x1400
	s_addc_u32 s5, s3, 0
	s_mov_b32 s96, 0xbfb8aa3b
	s_mov_b32 s97, 0x3f317217
	s_waitcnt vmcnt(0)
	v_readlane_b32 s72, v193, 32
	v_readlane_b32 s73, v193, 33
	v_readlane_b32 s74, v193, 34
	v_readlane_b32 s75, v193, 35
	v_readlane_b32 s76, v193, 36
	v_readlane_b32 s77, v193, 37
	v_readlane_b32 s78, v193, 38
	v_readlane_b32 s79, v193, 39
	s_lshl_b32 s80, s72, 16
	s_and_b32 s81, s72, 0xffff0000
	s_lshl_b32 s82, s73, 16
	s_and_b32 s83, s73, 0xffff0000
	s_lshl_b32 s84, s74, 16
	s_and_b32 s85, s74, 0xffff0000
	s_lshl_b32 s86, s75, 16
	s_and_b32 s87, s75, 0xffff0000
	s_lshl_b32 s88, s76, 16
	s_and_b32 s89, s76, 0xffff0000
	s_lshl_b32 s90, s77, 16
	s_and_b32 s91, s77, 0xffff0000
	s_lshl_b32 s92, s78, 16
	s_and_b32 s93, s78, 0xffff0000
	s_lshl_b32 s94, s79, 16
	s_and_b32 s95, s79, 0xffff0000
	v_fma_f32 v80, v182, s80, v186
	v_fma_f32 v81, v176, s80, v177
	v_fmac_f32_e32 v80, s81, v181
	v_fmac_f32_e32 v81, s81, v175
	v_fmac_f32_e32 v80, s82, v180
	v_fmac_f32_e32 v81, s82, v174
	v_fmac_f32_e32 v80, s83, v185
	v_fmac_f32_e32 v81, s83, v173
	v_fmac_f32_e32 v80, s84, v184
	v_fmac_f32_e32 v81, s84, v179
	v_fmac_f32_e32 v80, s85, v183
	v_fmac_f32_e32 v81, s85, v178
	v_fmac_f32_e32 v80, s86, v107
	v_fmac_f32_e32 v81, s86, v99
	v_fmac_f32_e32 v80, s87, v106
	v_fmac_f32_e32 v81, s87, v98
	v_fmac_f32_e32 v80, s88, v105
	v_fmac_f32_e32 v81, s88, v97
	v_fmac_f32_e32 v80, s89, v104
	v_fmac_f32_e32 v81, s89, v96
	v_fmac_f32_e32 v80, s90, v103
	v_fmac_f32_e32 v81, s90, v93
	v_fmac_f32_e32 v80, s91, v102
	v_fmac_f32_e32 v81, s91, v92
	v_fmac_f32_e32 v80, s92, v101
	v_fmac_f32_e32 v81, s92, v91
	v_fmac_f32_e32 v80, s93, v100
	v_fmac_f32_e32 v81, s93, v90
	v_fmac_f32_e32 v80, s94, v95
	v_fmac_f32_e32 v81, s94, v89
	v_fmac_f32_e32 v80, s95, v94
	v_fmac_f32_e32 v81, s95, v88
	v_mul_f32_e64 v82, |v80|, s96
	v_mul_f32_e64 v83, |v81|, s96
	v_exp_f32_e32 v82, v82
	v_exp_f32_e32 v83, v83
	v_min_f32_e32 v80, 0, v80
	v_min_f32_e32 v81, 0, v81
	v_add_f32_e32 v82, 1.0, v82
	v_add_f32_e32 v83, 1.0, v83
	v_log_f32_e32 v82, v82
	v_log_f32_e32 v83, v83
	s_nop 0
	v_mul_f32_e32 v116, 0x3f317217, v82
	v_mul_f32_e32 v117, 0x3f317217, v83
	v_fma_f32 v116, v82, s97, -v116
	v_fma_f32 v117, v83, s97, -v117
	v_fmac_f32_e32 v116, 0x3377d1cf, v82
	v_fmac_f32_e32 v117, 0x3377d1cf, v83
	v_fmac_f32_e32 v116, 0x3f317217, v82
	v_fmac_f32_e32 v117, 0x3f317217, v83
	v_sub_f32_e32 v80, v80, v116
	v_sub_f32_e32 v81, v81, v117
	v_mul_f32_e32 v116, 0x3d800000, v80
	v_mul_f32_e32 v117, 0x3d800000, v81
; template <bool FINAL>
; DI void gla_unit(KA a, int l, int item, LAS unsigned char* lds) {
;     ...
;         for (int jj = 0; jj < 8; ++jj) {
;             const int t = 8 * tg + jj;
;             float ga = 0.f, gb = 0.f;
;             if (t < nvalid) {
;                 const u32x4* lp = (const u32x4*)(U + (size_t)(row0 + t) * UN + U_LR);
;                 float lr[16]; unpack8(lp[0], lr); unpack8(lp[1], lr + 8);
;                 float za = bg[0], zb = bg[1];
; #pragma unroll
;                 for (int e = 0; e < 16; ++e) { za += wg[0][e] * lr[e]; zb += wg[1][e] * lr[e]; }
;                 ga = (fminf(za, 0.f) - __logf(1.f + __expf(-fabsf(za)))) * (1.f / 16.f);
;                 gb = (fminf(zb, 0.f) - __logf(1.f + __expf(-fabsf(zb)))) * (1.f / 16.f);
;             }
;             run0 += ga; run1 += gb; bl[0][jj] = run0; bl[1][jj] = run1;
.LBB0_895:
	s_and_b64 vcc, exec, s[14:15]
	v_mov_b32_e32 v115, 0
	s_cbranch_vccnz .LBB0_897
	s_add_i32 s0, s49, s46
	s_mul_hi_i32 s3, s0, 0x1600
	s_mulk_i32 s0, 0x1600
	s_add_u32 s2, s30, s0
	s_addc_u32 s3, s31, s3
	s_add_u32 s4, s2, 0x1400
	s_addc_u32 s5, s3, 0
	s_mov_b32 s96, 0xbfb8aa3b
	s_mov_b32 s97, 0x3f317217
	s_waitcnt vmcnt(0)
	v_readlane_b32 s72, v193, 40
	v_readlane_b32 s73, v193, 41
	v_readlane_b32 s74, v193, 42
	v_readlane_b32 s75, v193, 43
	v_readlane_b32 s76, v193, 44
	v_readlane_b32 s77, v193, 45
	v_readlane_b32 s78, v193, 46
	v_readlane_b32 s79, v193, 47
	s_lshl_b32 s80, s72, 16
	s_and_b32 s81, s72, 0xffff0000
	s_lshl_b32 s82, s73, 16
	s_and_b32 s83, s73, 0xffff0000
	s_lshl_b32 s84, s74, 16
	s_and_b32 s85, s74, 0xffff0000
	s_lshl_b32 s86, s75, 16
	s_and_b32 s87, s75, 0xffff0000
	s_lshl_b32 s88, s76, 16
	s_and_b32 s89, s76, 0xffff0000
	s_lshl_b32 s90, s77, 16
	s_and_b32 s91, s77, 0xffff0000
	s_lshl_b32 s92, s78, 16
	s_and_b32 s93, s78, 0xffff0000
	s_lshl_b32 s94, s79, 16
	s_and_b32 s95, s79, 0xffff0000
	v_fma_f32 v80, v182, s80, v186
	v_fma_f32 v81, v176, s80, v177
	v_fmac_f32_e32 v80, s81, v181
	v_fmac_f32_e32 v81, s81, v175
	v_fmac_f32_e32 v80, s82, v180
	v_fmac_f32_e32 v81, s82, v174
	v_fmac_f32_e32 v80, s83, v185
	v_fmac_f32_e32 v81, s83, v173
	v_fmac_f32_e32 v80, s84, v184
	v_fmac_f32_e32 v81, s84, v179
	v_fmac_f32_e32 v80, s85, v183
	v_fmac_f32_e32 v81, s85, v178
	v_fmac_f32_e32 v80, s86, v107
	v_fmac_f32_e32 v81, s86, v99
	v_fmac_f32_e32 v80, s87, v106
	v_fmac_f32_e32 v81, s87, v98
	v_fmac_f32_e32 v80, s88, v105
	v_fmac_f32_e32 v81, s88, v97
	v_fmac_f32_e32 v80, s89, v104
	v_fmac_f32_e32 v81, s89, v96
	v_fmac_f32_e32 v80, s90, v103
	v_fmac_f32_e32 v81, s90, v93
	v_fmac_f32_e32 v80, s91, v102
	v_fmac_f32_e32 v81, s91, v92
	v_fmac_f32_e32 v80, s92, v101
	v_fmac_f32_e32 v81, s92, v91
	v_fmac_f32_e32 v80, s93, v100
	v_fmac_f32_e32 v81, s93, v90
	v_fmac_f32_e32 v80, s94, v95
	v_fmac_f32_e32 v81, s94, v89
	v_fmac_f32_e32 v80, s95, v94
	v_fmac_f32_e32 v81, s95, v88
	v_mul_f32_e64 v82, |v80|, s96
	v_mul_f32_e64 v83, |v81|, s96
	v_exp_f32_e32 v82, v82
	v_exp_f32_e32 v83, v83
	v_min_f32_e32 v80, 0, v80
	v_min_f32_e32 v81, 0, v81
	v_add_f32_e32 v82, 1.0, v82
	v_add_f32_e32 v83, 1.0, v83
	v_log_f32_e32 v82, v82
	v_log_f32_e32 v83, v83
	s_nop 0
	v_mul_f32_e32 v114, 0x3f317217, v82
	v_mul_f32_e32 v115, 0x3f317217, v83
	v_fma_f32 v114, v82, s97, -v114
	v_fma_f32 v115, v83, s97, -v115
	v_fmac_f32_e32 v114, 0x3377d1cf, v82
	v_fmac_f32_e32 v115, 0x3377d1cf, v83
	v_fmac_f32_e32 v114, 0x3f317217, v82
	v_fmac_f32_e32 v115, 0x3f317217, v83
	v_sub_f32_e32 v80, v80, v114
	v_sub_f32_e32 v81, v81, v115
	v_mul_f32_e32 v114, 0x3d800000, v80
	v_mul_f32_e32 v115, 0x3d800000, v81
; template <bool FINAL>
; DI void gla_unit(KA a, int l, int item, LAS unsigned char* lds) {
;     ...
;         for (int jj = 0; jj < 8; ++jj) {
;             const int t = 8 * tg + jj;
;             float ga = 0.f, gb = 0.f;
;             if (t < nvalid) {
;                 const u32x4* lp = (const u32x4*)(U + (size_t)(row0 + t) * UN + U_LR);
;                 float lr[16]; unpack8(lp[0], lr); unpack8(lp[1], lr + 8);
;                 float za = bg[0], zb = bg[1];
; #pragma unroll
;                 for (int e = 0; e < 16; ++e) { za += wg[0][e] * lr[e]; zb += wg[1][e] * lr[e]; }
;                 ga = (fminf(za, 0.f) - __logf(1.f + __expf(-fabsf(za)))) * (1.f / 16.f);
;                 gb = (fminf(zb, 0.f) - __logf(1.f + __expf(-fabsf(zb)))) * (1.f / 16.f);
;             }
;             run0 += ga; run1 += gb; bl[0][jj] = run0; bl[1][jj] = run1;
.LBB0_897:
	v_mov_b32_e32 v118, 0
	s_and_b64 vcc, exec, s[12:13]
	v_mov_b32_e32 v120, 0
	v_mov_b32_e32 v121, 0
	s_cbranch_vccnz .LBB0_899
	s_add_i32 s0, s48, s46
	s_mul_hi_i32 s3, s0, 0x1600
	s_mulk_i32 s0, 0x1600
	s_add_u32 s2, s30, s0
	s_addc_u32 s3, s31, s3
	s_add_u32 s4, s2, 0x1400
	s_addc_u32 s5, s3, 0
	s_mov_b32 s96, 0xbfb8aa3b
	s_mov_b32 s97, 0x3f317217
	s_waitcnt vmcnt(0)
	v_readlane_b32 s72, v193, 48
	v_readlane_b32 s73, v193, 49
	v_readlane_b32 s74, v193, 50
	v_readlane_b32 s75, v193, 51
	v_readlane_b32 s76, v193, 52
	v_readlane_b32 s77, v193, 53
	v_readlane_b32 s78, v193, 54
	v_readlane_b32 s79, v193, 55
	s_lshl_b32 s80, s72, 16
	s_and_b32 s81, s72, 0xffff0000
	s_lshl_b32 s82, s73, 16
	s_and_b32 s83, s73, 0xffff0000
	s_lshl_b32 s84, s74, 16
	s_and_b32 s85, s74, 0xffff0000
	s_lshl_b32 s86, s75, 16
	s_and_b32 s87, s75, 0xffff0000
	s_lshl_b32 s88, s76, 16
	s_and_b32 s89, s76, 0xffff0000
	s_lshl_b32 s90, s77, 16
	s_and_b32 s91, s77, 0xffff0000
	s_lshl_b32 s92, s78, 16
	s_and_b32 s93, s78, 0xffff0000
	s_lshl_b32 s94, s79, 16
	s_and_b32 s95, s79, 0xffff0000
	v_fma_f32 v80, v182, s80, v186
	v_fma_f32 v81, v176, s80, v177
	v_fmac_f32_e32 v80, s81, v181
	v_fmac_f32_e32 v81, s81, v175
	v_fmac_f32_e32 v80, s82, v180
	v_fmac_f32_e32 v81, s82, v174
	v_fmac_f32_e32 v80, s83, v185
	v_fmac_f32_e32 v81, s83, v173
	v_fmac_f32_e32 v80, s84, v184
	v_fmac_f32_e32 v81, s84, v179
	v_fmac_f32_e32 v80, s85, v183
	v_fmac_f32_e32 v81, s85, v178
	v_fmac_f32_e32 v80, s86, v107
	v_fmac_f32_e32 v81, s86, v99
	v_fmac_f32_e32 v80, s87, v106
	v_fmac_f32_e32 v81, s87, v98
	v_fmac_f32_e32 v80, s88, v105
	v_fmac_f32_e32 v81, s88, v97
	v_fmac_f32_e32 v80, s89, v104
	v_fmac_f32_e32 v81, s89, v96
	v_fmac_f32_e32 v80, s90, v103
	v_fmac_f32_e32 v81, s90, v93
	v_fmac_f32_e32 v80, s91, v102
	v_fmac_f32_e32 v81, s91, v92
	v_fmac_f32_e32 v80, s92, v101
	v_fmac_f32_e32 v81, s92, v91
	v_fmac_f32_e32 v80, s93, v100
	v_fmac_f32_e32 v81, s93, v90
	v_fmac_f32_e32 v80, s94, v95
	v_fmac_f32_e32 v81, s94, v89
	v_fmac_f32_e32 v80, s95, v94
	v_fmac_f32_e32 v81, s95, v88
	v_mul_f32_e64 v82, |v80|, s96
	v_mul_f32_e64 v83, |v81|, s96
	v_exp_f32_e32 v82, v82
	v_exp_f32_e32 v83, v83
	v_min_f32_e32 v80, 0, v80
	v_min_f32_e32 v81, 0, v81
	v_add_f32_e32 v82, 1.0, v82
	v_add_f32_e32 v83, 1.0, v83
	v_log_f32_e32 v82, v82
	v_log_f32_e32 v83, v83
	s_nop 0
	v_mul_f32_e32 v120, 0x3f317217, v82
	v_mul_f32_e32 v121, 0x3f317217, v83
	v_fma_f32 v120, v82, s97, -v120
	v_fma_f32 v121, v83, s97, -v121
	v_fmac_f32_e32 v120, 0x3377d1cf, v82
	v_fmac_f32_e32 v121, 0x3377d1cf, v83
	v_fmac_f32_e32 v120, 0x3f317217, v82
	v_fmac_f32_e32 v121, 0x3f317217, v83
	v_sub_f32_e32 v80, v80, v120
	v_sub_f32_e32 v81, v81, v121
	v_mul_f32_e32 v120, 0x3d800000, v80
	v_mul_f32_e32 v121, 0x3d800000, v81
.LBB0_899:
	s_and_b64 vcc, exec, s[10:11]
	v_mov_b32_e32 v119, 0
	s_cbranch_vccnz .LBB0_901
	s_add_i32 s0, s47, s46
	s_mul_hi_i32 s3, s0, 0x1600
	s_mulk_i32 s0, 0x1600
	s_add_u32 s2, s30, s0
	s_addc_u32 s3, s31, s3
	s_add_u32 s4, s2, 0x1400
	s_addc_u32 s5, s3, 0
	s_mov_b32 s96, 0xbfb8aa3b
	s_mov_b32 s97, 0x3f317217
	s_waitcnt vmcnt(0)
	v_readlane_b32 s72, v193, 56
	v_readlane_b32 s73, v193, 57
	v_readlane_b32 s74, v193, 58
	v_readlane_b32 s75, v193, 59
	v_readlane_b32 s76, v193, 60
	v_readlane_b32 s77, v193, 61
	v_readlane_b32 s78, v193, 62
	v_readlane_b32 s79, v193, 63
	s_lshl_b32 s80, s72, 16
	s_and_b32 s81, s72, 0xffff0000
	s_lshl_b32 s82, s73, 16
	s_and_b32 s83, s73, 0xffff0000
	s_lshl_b32 s84, s74, 16
	s_and_b32 s85, s74, 0xffff0000
	s_lshl_b32 s86, s75, 16
	s_and_b32 s87, s75, 0xffff0000
	s_lshl_b32 s88, s76, 16
	s_and_b32 s89, s76, 0xffff0000
	s_lshl_b32 s90, s77, 16
	s_and_b32 s91, s77, 0xffff0000
	s_lshl_b32 s92, s78, 16
	s_and_b32 s93, s78, 0xffff0000
	s_lshl_b32 s94, s79, 16
	s_and_b32 s95, s79, 0xffff0000
	v_fma_f32 v80, v182, s80, v186
	v_fma_f32 v81, v176, s80, v177
	v_fmac_f32_e32 v80, s81, v181
	v_fmac_f32_e32 v81, s81, v175
	v_fmac_f32_e32 v80, s82, v180
	v_fmac_f32_e32 v81, s82, v174
	v_fmac_f32_e32 v80, s83, v185
	v_fmac_f32_e32 v81, s83, v173
	v_fmac_f32_e32 v80, s84, v184
	v_fmac_f32_e32 v81, s84, v179
	v_fmac_f32_e32 v80, s85, v183
	v_fmac_f32_e32 v81, s85, v178
	v_fmac_f32_e32 v80, s86, v107
	v_fmac_f32_e32 v81, s86, v99
	v_fmac_f32_e32 v80, s87, v106
	v_fmac_f32_e32 v81, s87, v98
	v_fmac_f32_e32 v80, s88, v105
	v_fmac_f32_e32 v81, s88, v97
	v_fmac_f32_e32 v80, s89, v104
	v_fmac_f32_e32 v81, s89, v96
	v_fmac_f32_e32 v80, s90, v103
	v_fmac_f32_e32 v81, s90, v93
	v_fmac_f32_e32 v80, s91, v102
	v_fmac_f32_e32 v81, s91, v92
	v_fmac_f32_e32 v80, s92, v101
	v_fmac_f32_e32 v81, s92, v91
	v_fmac_f32_e32 v80, s93, v100
	v_fmac_f32_e32 v81, s93, v90
	v_fmac_f32_e32 v80, s94, v95
	v_fmac_f32_e32 v81, s94, v89
	v_fmac_f32_e32 v80, s95, v94
	v_fmac_f32_e32 v81, s95, v88
	v_mul_f32_e64 v82, |v80|, s96
	v_mul_f32_e64 v83, |v81|, s96
	v_exp_f32_e32 v82, v82
	v_exp_f32_e32 v83, v83
	v_min_f32_e32 v80, 0, v80
	v_min_f32_e32 v81, 0, v81
	v_add_f32_e32 v82, 1.0, v82
	v_add_f32_e32 v83, 1.0, v83
	v_log_f32_e32 v82, v82
	v_log_f32_e32 v83, v83
	s_nop 0
	v_mul_f32_e32 v118, 0x3f317217, v82
	v_mul_f32_e32 v119, 0x3f317217, v83
	v_fma_f32 v118, v82, s97, -v118
	v_fma_f32 v119, v83, s97, -v119
	v_fmac_f32_e32 v118, 0x3377d1cf, v82
	v_fmac_f32_e32 v119, 0x3377d1cf, v83
	v_fmac_f32_e32 v118, 0x3f317217, v82
	v_fmac_f32_e32 v119, 0x3f317217, v83
	v_sub_f32_e32 v80, v80, v118
	v_sub_f32_e32 v81, v81, v119
	v_mul_f32_e32 v118, 0x3d800000, v80
	v_mul_f32_e32 v119, 0x3d800000, v81
